# grid barrier: non-leader workgroups poll the cross-XCD release generation directly (skips the per-XCD relay hop)
# baseline (speedup 1.0000x reference)
; __device__ __forceinline__ unsigned xb_ld(unsigned* p)              { return __hip_atomic_load(p, __ATOMIC_RELAXED, __HIP_MEMORY_SCOPE_AGENT); }
; __device__ __forceinline__ unsigned xb_add(unsigned* p, unsigned v) { return __hip_atomic_fetch_add(p, v, __ATOMIC_RELAXED, __HIP_MEMORY_SCOPE_AGENT); }
; #define XB_SPIN(cond, bar) do { unsigned _sp = 0; while (cond) { __builtin_amdgcn_s_sleep(1); \
;     if ((++_sp & 255u) == 0u) { if (xb_ld(&(bar)[XB_TMO])) break; if (_sp > XB_SPIN_CAP) { atomicAdd(&(bar)[XB_TMO], 1u); break; } } } } while (0)
; __device__ __forceinline__ void xcd_barrier(const XcdBarrier& b) {
;     ...
;         const unsigned old = xb_add(&bar[XB_XSUB(b.x)], 1u);
;         const unsigned gen = old / nloc;
;         if (old + 1u == (gen + 1u) * nloc) {
;             __builtin_amdgcn_fence(__ATOMIC_RELEASE, "agent");
;             asm volatile("s_waitcnt vmcnt(0)" ::: "memory");
;             const unsigned og = xb_add(&bar[XB_TOP], 1u);
;             const unsigned tg = og / nx;
;             if (og + 1u == (tg + 1u) * nx) xb_add(&bar[XB_TOPGEN], 1u);
;             else XB_SPIN(xb_ld(&bar[XB_TOPGEN]) == tg, bar);
;             __builtin_amdgcn_fence(__ATOMIC_ACQUIRE, "agent");
;             xb_add(&bar[XB_XGEN(b.x)], 1u);
;             asm volatile("s_waitcnt vmcnt(0)" ::: "memory");
;         } else {
;             XB_SPIN(xb_ld(&bar[XB_XGEN(b.x)]) == gen, bar);
.LBB0_279:
	s_or_b64 exec, exec, s[6:7]
	v_cvt_f32_u32_e32 v4, v2
	s_waitcnt vmcnt(0)
	v_readfirstlane_b32 s4, v3
	v_sub_u32_e32 v3, 0, v2
	v_rcp_iflag_f32_e32 v4, v4
	v_add_u32_e32 v5, s4, v1
	v_mul_f32_e32 v4, 0x4f7ffffe, v4
	v_cvt_u32_f32_e32 v4, v4
	v_mul_lo_u32 v1, v3, v4
	v_mul_hi_u32 v1, v4, v1
	v_add_u32_e32 v1, v4, v1
	v_mul_hi_u32 v1, v5, v1
	v_mul_lo_u32 v3, v1, v2
	v_sub_u32_e32 v3, v5, v3
	v_add_u32_e32 v4, 1, v1
	v_cmp_ge_u32_e32 vcc, v3, v2
	s_nop 1
	v_cndmask_b32_e32 v1, v1, v4, vcc
	v_sub_u32_e32 v4, v3, v2
	v_cndmask_b32_e32 v3, v3, v4, vcc
	v_add_u32_e32 v4, 1, v1
	v_cmp_ge_u32_e32 vcc, v3, v2
	v_add_u32_e32 v3, 1, v5
	s_nop 0
	v_cndmask_b32_e32 v1, v1, v4, vcc
	v_mul_lo_u32 v4, v2, v1
	v_add_u32_e32 v2, v4, v2
	v_cmp_ne_u32_e32 vcc, v3, v2
	s_and_saveexec_b64 s[4:5], vcc
	s_xor_b64 s[4:5], exec, s[4:5]
	s_cbranch_execz .LBB0_293
	s_waitcnt lgkmcnt(0)
	v_mov_b32_e32 v0, 0x6703500
	global_load_dword v0, v0, s[86:87] sc1
	s_add_u32 s10, s86, 0x6703500
	s_addc_u32 s11, s87, 0
	s_waitcnt vmcnt(0)
	v_cmp_eq_u32_e32 vcc, v0, v1
	s_and_saveexec_b64 s[6:7], vcc
	s_cbranch_execz .LBB0_292
	s_add_u32 s8, s86, 0x6700200
	s_addc_u32 s9, s87, 0
	s_mov_b32 s14, 1
	s_mov_b64 s[16:17], 0
	v_mov_b32_e32 v0, 0
	s_branch .LBB0_283

; __device__ __forceinline__ unsigned xb_ld(unsigned* p)              { return __hip_atomic_load(p, __ATOMIC_RELAXED, __HIP_MEMORY_SCOPE_AGENT); }
; __device__ __forceinline__ unsigned xb_add(unsigned* p, unsigned v) { return __hip_atomic_fetch_add(p, v, __ATOMIC_RELAXED, __HIP_MEMORY_SCOPE_AGENT); }
; #define XB_SPIN(cond, bar) do { unsigned _sp = 0; while (cond) { __builtin_amdgcn_s_sleep(1); \
;     if ((++_sp & 255u) == 0u) { if (xb_ld(&(bar)[XB_TMO])) break; if (_sp > XB_SPIN_CAP) { atomicAdd(&(bar)[XB_TMO], 1u); break; } } } } while (0)
; __device__ __forceinline__ void xcd_barrier(const XcdBarrier& b) {
;     ...
;         const unsigned old = xb_add(&bar[XB_XSUB(b.x)], 1u);
;         const unsigned gen = old / nloc;
;         if (old + 1u == (gen + 1u) * nloc) {
;             __builtin_amdgcn_fence(__ATOMIC_RELEASE, "agent");
;             asm volatile("s_waitcnt vmcnt(0)" ::: "memory");
;             const unsigned og = xb_add(&bar[XB_TOP], 1u);
;             const unsigned tg = og / nx;
;             if (og + 1u == (tg + 1u) * nx) xb_add(&bar[XB_TOPGEN], 1u);
;             else XB_SPIN(xb_ld(&bar[XB_TOPGEN]) == tg, bar);
;             __builtin_amdgcn_fence(__ATOMIC_ACQUIRE, "agent");
;             xb_add(&bar[XB_XGEN(b.x)], 1u);
;             asm volatile("s_waitcnt vmcnt(0)" ::: "memory");
;         } else {
;             XB_SPIN(xb_ld(&bar[XB_XGEN(b.x)]) == gen, bar);
.LBB0_361:
	s_or_b64 exec, exec, s[8:9]
	v_cvt_f32_u32_e32 v4, v2
	s_waitcnt vmcnt(0)
	v_readfirstlane_b32 s6, v3
	v_sub_u32_e32 v3, 0, v2
	v_rcp_iflag_f32_e32 v4, v4
	v_add_u32_e32 v5, s6, v1
	v_mul_f32_e32 v4, 0x4f7ffffe, v4
	v_cvt_u32_f32_e32 v4, v4
	v_mul_lo_u32 v1, v3, v4
	v_mul_hi_u32 v1, v4, v1
	v_add_u32_e32 v1, v4, v1
	v_mul_hi_u32 v1, v5, v1
	v_mul_lo_u32 v3, v1, v2
	v_sub_u32_e32 v3, v5, v3
	v_add_u32_e32 v4, 1, v1
	v_cmp_ge_u32_e32 vcc, v3, v2
	s_nop 1
	v_cndmask_b32_e32 v1, v1, v4, vcc
	v_sub_u32_e32 v4, v3, v2
	v_cndmask_b32_e32 v3, v3, v4, vcc
	v_add_u32_e32 v4, 1, v1
	v_cmp_ge_u32_e32 vcc, v3, v2
	v_add_u32_e32 v3, 1, v5
	s_nop 0
	v_cndmask_b32_e32 v1, v1, v4, vcc
	v_mul_lo_u32 v4, v2, v1
	v_add_u32_e32 v2, v4, v2
	v_cmp_ne_u32_e32 vcc, v3, v2
	s_and_saveexec_b64 s[6:7], vcc
	s_xor_b64 s[6:7], exec, s[6:7]
	s_cbranch_execz .LBB0_375
	s_waitcnt lgkmcnt(0)
	v_mov_b32_e32 v0, 0x6703500
	global_load_dword v0, v0, s[86:87] sc1
	s_add_u32 s12, s86, 0x6703500
	s_addc_u32 s13, s87, 0
	s_waitcnt vmcnt(0)
	v_cmp_eq_u32_e32 vcc, v0, v1
	s_and_saveexec_b64 s[8:9], vcc
	s_cbranch_execz .LBB0_374
	s_add_u32 s10, s86, 0x6700200
	s_addc_u32 s11, s87, 0
	s_mov_b32 s14, 1
	s_mov_b64 s[42:43], 0
	v_mov_b32_e32 v0, 0
	s_branch .LBB0_365

; __device__ __forceinline__ unsigned xb_ld(unsigned* p)              { return __hip_atomic_load(p, __ATOMIC_RELAXED, __HIP_MEMORY_SCOPE_AGENT); }
; __device__ __forceinline__ unsigned xb_add(unsigned* p, unsigned v) { return __hip_atomic_fetch_add(p, v, __ATOMIC_RELAXED, __HIP_MEMORY_SCOPE_AGENT); }
; #define XB_SPIN(cond, bar) do { unsigned _sp = 0; while (cond) { __builtin_amdgcn_s_sleep(1); \
;     if ((++_sp & 255u) == 0u) { if (xb_ld(&(bar)[XB_TMO])) break; if (_sp > XB_SPIN_CAP) { atomicAdd(&(bar)[XB_TMO], 1u); break; } } } } while (0)
; __device__ __forceinline__ void xcd_barrier(const XcdBarrier& b) {
;     ...
;         const unsigned old = xb_add(&bar[XB_XSUB(b.x)], 1u);
;         const unsigned gen = old / nloc;
;         if (old + 1u == (gen + 1u) * nloc) {
;             __builtin_amdgcn_fence(__ATOMIC_RELEASE, "agent");
;             asm volatile("s_waitcnt vmcnt(0)" ::: "memory");
;             const unsigned og = xb_add(&bar[XB_TOP], 1u);
;             const unsigned tg = og / nx;
;             if (og + 1u == (tg + 1u) * nx) xb_add(&bar[XB_TOPGEN], 1u);
;             else XB_SPIN(xb_ld(&bar[XB_TOPGEN]) == tg, bar);
;             __builtin_amdgcn_fence(__ATOMIC_ACQUIRE, "agent");
;             xb_add(&bar[XB_XGEN(b.x)], 1u);
;             asm volatile("s_waitcnt vmcnt(0)" ::: "memory");
;         } else {
;             XB_SPIN(xb_ld(&bar[XB_XGEN(b.x)]) == gen, bar);
.LBB0_557:
	s_or_b64 exec, exec, s[8:9]
	v_cvt_f32_u32_e32 v4, v2
	s_waitcnt vmcnt(0)
	v_readfirstlane_b32 s6, v3
	v_sub_u32_e32 v3, 0, v2
	v_rcp_iflag_f32_e32 v4, v4
	v_add_u32_e32 v5, s6, v1
	v_mul_f32_e32 v4, 0x4f7ffffe, v4
	v_cvt_u32_f32_e32 v4, v4
	v_mul_lo_u32 v1, v3, v4
	v_mul_hi_u32 v1, v4, v1
	v_add_u32_e32 v1, v4, v1
	v_mul_hi_u32 v1, v5, v1
	v_mul_lo_u32 v3, v1, v2
	v_sub_u32_e32 v3, v5, v3
	v_add_u32_e32 v4, 1, v1
	v_cmp_ge_u32_e32 vcc, v3, v2
	s_nop 1
	v_cndmask_b32_e32 v1, v1, v4, vcc
	v_sub_u32_e32 v4, v3, v2
	v_cndmask_b32_e32 v3, v3, v4, vcc
	v_add_u32_e32 v4, 1, v1
	v_cmp_ge_u32_e32 vcc, v3, v2
	v_add_u32_e32 v3, 1, v5
	s_nop 0
	v_cndmask_b32_e32 v1, v1, v4, vcc
	v_mul_lo_u32 v4, v2, v1
	v_add_u32_e32 v2, v4, v2
	v_cmp_ne_u32_e32 vcc, v3, v2
	s_and_saveexec_b64 s[6:7], vcc
	s_xor_b64 s[6:7], exec, s[6:7]
	s_cbranch_execz .LBB0_571
	s_waitcnt lgkmcnt(0)
	v_mov_b32_e32 v0, 0x6703500
	global_load_dword v0, v0, s[86:87] sc1
	s_add_u32 s12, s86, 0x6703500
	s_addc_u32 s13, s87, 0
	s_waitcnt vmcnt(0)
	v_cmp_eq_u32_e32 vcc, v0, v1
	s_and_saveexec_b64 s[8:9], vcc
	s_cbranch_execz .LBB0_570
	s_add_u32 s10, s86, 0x6700200
	s_addc_u32 s11, s87, 0
	s_mov_b32 s14, 1
	s_mov_b64 s[46:47], 0
	v_mov_b32_e32 v0, 0
	s_branch .LBB0_561

; __device__ __forceinline__ unsigned xb_ld(unsigned* p)              { return __hip_atomic_load(p, __ATOMIC_RELAXED, __HIP_MEMORY_SCOPE_AGENT); }
; __device__ __forceinline__ unsigned xb_add(unsigned* p, unsigned v) { return __hip_atomic_fetch_add(p, v, __ATOMIC_RELAXED, __HIP_MEMORY_SCOPE_AGENT); }
; #define XB_SPIN(cond, bar) do { unsigned _sp = 0; while (cond) { __builtin_amdgcn_s_sleep(1); \
;     if ((++_sp & 255u) == 0u) { if (xb_ld(&(bar)[XB_TMO])) break; if (_sp > XB_SPIN_CAP) { atomicAdd(&(bar)[XB_TMO], 1u); break; } } } } while (0)
; __device__ __forceinline__ void xcd_barrier(const XcdBarrier& b) {
;     ...
;         const unsigned old = xb_add(&bar[XB_XSUB(b.x)], 1u);
;         const unsigned gen = old / nloc;
;         if (old + 1u == (gen + 1u) * nloc) {
;             __builtin_amdgcn_fence(__ATOMIC_RELEASE, "agent");
;             asm volatile("s_waitcnt vmcnt(0)" ::: "memory");
;             const unsigned og = xb_add(&bar[XB_TOP], 1u);
;             const unsigned tg = og / nx;
;             if (og + 1u == (tg + 1u) * nx) xb_add(&bar[XB_TOPGEN], 1u);
;             else XB_SPIN(xb_ld(&bar[XB_TOPGEN]) == tg, bar);
;             __builtin_amdgcn_fence(__ATOMIC_ACQUIRE, "agent");
;             xb_add(&bar[XB_XGEN(b.x)], 1u);
;             asm volatile("s_waitcnt vmcnt(0)" ::: "memory");
;         } else {
;             XB_SPIN(xb_ld(&bar[XB_XGEN(b.x)]) == gen, bar);
.LBB0_824:
	s_or_b64 exec, exec, s[8:9]
	v_cvt_f32_u32_e32 v4, v2
	s_waitcnt vmcnt(0)
	v_readfirstlane_b32 s6, v3
	v_sub_u32_e32 v3, 0, v2
	v_rcp_iflag_f32_e32 v4, v4
	v_add_u32_e32 v5, s6, v1
	v_mul_f32_e32 v4, 0x4f7ffffe, v4
	v_cvt_u32_f32_e32 v4, v4
	v_mul_lo_u32 v1, v3, v4
	v_mul_hi_u32 v1, v4, v1
	v_add_u32_e32 v1, v4, v1
	v_mul_hi_u32 v1, v5, v1
	v_mul_lo_u32 v3, v1, v2
	v_sub_u32_e32 v3, v5, v3
	v_add_u32_e32 v4, 1, v1
	v_cmp_ge_u32_e32 vcc, v3, v2
	s_nop 1
	v_cndmask_b32_e32 v1, v1, v4, vcc
	v_sub_u32_e32 v4, v3, v2
	v_cndmask_b32_e32 v3, v3, v4, vcc
	v_add_u32_e32 v4, 1, v1
	v_cmp_ge_u32_e32 vcc, v3, v2
	v_add_u32_e32 v3, 1, v5
	s_nop 0
	v_cndmask_b32_e32 v1, v1, v4, vcc
	v_mul_lo_u32 v4, v2, v1
	v_add_u32_e32 v2, v4, v2
	v_cmp_ne_u32_e32 vcc, v3, v2
	s_and_saveexec_b64 s[6:7], vcc
	s_xor_b64 s[6:7], exec, s[6:7]
	s_cbranch_execz .LBB0_838
	s_waitcnt lgkmcnt(0)
	v_mov_b32_e32 v0, 0x6703500
	global_load_dword v0, v0, s[86:87] sc1
	s_add_u32 s12, s86, 0x6703500
	s_addc_u32 s13, s87, 0
	s_waitcnt vmcnt(0)
	v_cmp_eq_u32_e32 vcc, v0, v1
	s_and_saveexec_b64 s[8:9], vcc
	s_cbranch_execz .LBB0_837
	s_add_u32 s10, s86, 0x6700200
	s_addc_u32 s11, s87, 0
	s_mov_b32 s14, 1
	s_mov_b64 s[22:23], 0
	v_mov_b32_e32 v0, 0
	s_branch .LBB0_828

; __device__ __forceinline__ unsigned xb_ld(unsigned* p)              { return __hip_atomic_load(p, __ATOMIC_RELAXED, __HIP_MEMORY_SCOPE_AGENT); }
; __device__ __forceinline__ unsigned xb_add(unsigned* p, unsigned v) { return __hip_atomic_fetch_add(p, v, __ATOMIC_RELAXED, __HIP_MEMORY_SCOPE_AGENT); }
; #define XB_SPIN(cond, bar) do { unsigned _sp = 0; while (cond) { __builtin_amdgcn_s_sleep(1); \
;     if ((++_sp & 255u) == 0u) { if (xb_ld(&(bar)[XB_TMO])) break; if (_sp > XB_SPIN_CAP) { atomicAdd(&(bar)[XB_TMO], 1u); break; } } } } while (0)
; __device__ __forceinline__ void xcd_barrier(const XcdBarrier& b) {
;     ...
;         const unsigned old = xb_add(&bar[XB_XSUB(b.x)], 1u);
;         const unsigned gen = old / nloc;
;         if (old + 1u == (gen + 1u) * nloc) {
;             __builtin_amdgcn_fence(__ATOMIC_RELEASE, "agent");
;             asm volatile("s_waitcnt vmcnt(0)" ::: "memory");
;             const unsigned og = xb_add(&bar[XB_TOP], 1u);
;             const unsigned tg = og / nx;
;             if (og + 1u == (tg + 1u) * nx) xb_add(&bar[XB_TOPGEN], 1u);
;             else XB_SPIN(xb_ld(&bar[XB_TOPGEN]) == tg, bar);
;             __builtin_amdgcn_fence(__ATOMIC_ACQUIRE, "agent");
;             xb_add(&bar[XB_XGEN(b.x)], 1u);
;             asm volatile("s_waitcnt vmcnt(0)" ::: "memory");
;         } else {
;             XB_SPIN(xb_ld(&bar[XB_XGEN(b.x)]) == gen, bar);
.LBB0_943:
	s_or_b64 exec, exec, s[22:23]
	v_cvt_f32_u32_e32 v4, v2
	s_waitcnt vmcnt(0)
	v_readfirstlane_b32 s12, v3
	v_sub_u32_e32 v3, 0, v2
	v_rcp_iflag_f32_e32 v4, v4
	v_add_u32_e32 v5, s12, v1
	v_mul_f32_e32 v4, 0x4f7ffffe, v4
	v_cvt_u32_f32_e32 v4, v4
	v_mul_lo_u32 v1, v3, v4
	v_mul_hi_u32 v1, v4, v1
	v_add_u32_e32 v1, v4, v1
	v_mul_hi_u32 v1, v5, v1
	v_mul_lo_u32 v3, v1, v2
	v_sub_u32_e32 v3, v5, v3
	v_add_u32_e32 v4, 1, v1
	v_cmp_ge_u32_e32 vcc, v3, v2
	s_nop 1
	v_cndmask_b32_e32 v1, v1, v4, vcc
	v_sub_u32_e32 v4, v3, v2
	v_cndmask_b32_e32 v3, v3, v4, vcc
	v_add_u32_e32 v4, 1, v1
	v_cmp_ge_u32_e32 vcc, v3, v2
	v_add_u32_e32 v3, 1, v5
	s_nop 0
	v_cndmask_b32_e32 v1, v1, v4, vcc
	v_mul_lo_u32 v4, v2, v1
	v_add_u32_e32 v2, v4, v2
	v_cmp_ne_u32_e32 vcc, v3, v2
	s_and_saveexec_b64 s[12:13], vcc
	s_xor_b64 s[12:13], exec, s[12:13]
	s_cbranch_execz .LBB0_957
	s_waitcnt lgkmcnt(0)
	v_mov_b32_e32 v0, 0x6703500
	global_load_dword v0, v0, s[86:87] sc1
	s_add_u32 s26, s86, 0x6703500
	s_addc_u32 s27, s87, 0
	s_waitcnt vmcnt(0)
	v_cmp_eq_u32_e32 vcc, v0, v1
	s_and_saveexec_b64 s[22:23], vcc
	s_cbranch_execz .LBB0_956
	s_add_u32 s24, s86, 0x6700200
	s_addc_u32 s25, s87, 0
	s_mov_b32 s14, 1
	s_mov_b64 s[28:29], 0
	v_mov_b32_e32 v0, 0
	s_branch .LBB0_947

; __device__ __forceinline__ unsigned xb_ld(unsigned* p)              { return __hip_atomic_load(p, __ATOMIC_RELAXED, __HIP_MEMORY_SCOPE_AGENT); }
; __device__ __forceinline__ unsigned xb_add(unsigned* p, unsigned v) { return __hip_atomic_fetch_add(p, v, __ATOMIC_RELAXED, __HIP_MEMORY_SCOPE_AGENT); }
; #define XB_SPIN(cond, bar) do { unsigned _sp = 0; while (cond) { __builtin_amdgcn_s_sleep(1); \
;     if ((++_sp & 255u) == 0u) { if (xb_ld(&(bar)[XB_TMO])) break; if (_sp > XB_SPIN_CAP) { atomicAdd(&(bar)[XB_TMO], 1u); break; } } } } while (0)
; __device__ __forceinline__ void xcd_barrier(const XcdBarrier& b) {
;     ...
;         const unsigned old = xb_add(&bar[XB_XSUB(b.x)], 1u);
;         const unsigned gen = old / nloc;
;         if (old + 1u == (gen + 1u) * nloc) {
;             __builtin_amdgcn_fence(__ATOMIC_RELEASE, "agent");
;             asm volatile("s_waitcnt vmcnt(0)" ::: "memory");
;             const unsigned og = xb_add(&bar[XB_TOP], 1u);
;             const unsigned tg = og / nx;
;             if (og + 1u == (tg + 1u) * nx) xb_add(&bar[XB_TOPGEN], 1u);
;             else XB_SPIN(xb_ld(&bar[XB_TOPGEN]) == tg, bar);
;             __builtin_amdgcn_fence(__ATOMIC_ACQUIRE, "agent");
;             xb_add(&bar[XB_XGEN(b.x)], 1u);
;             asm volatile("s_waitcnt vmcnt(0)" ::: "memory");
;         } else {
;             XB_SPIN(xb_ld(&bar[XB_XGEN(b.x)]) == gen, bar);
.LBB0_1015:
	s_or_b64 exec, exec, s[24:25]
	v_cvt_f32_u32_e32 v4, v2
	s_waitcnt vmcnt(0)
	v_readfirstlane_b32 s14, v3
	v_sub_u32_e32 v3, 0, v2
	v_rcp_iflag_f32_e32 v4, v4
	v_add_u32_e32 v5, s14, v1
	v_mul_f32_e32 v4, 0x4f7ffffe, v4
	v_cvt_u32_f32_e32 v4, v4
	v_mul_lo_u32 v1, v3, v4
	v_mul_hi_u32 v1, v4, v1
	v_add_u32_e32 v1, v4, v1
	v_mul_hi_u32 v1, v5, v1
	v_mul_lo_u32 v3, v1, v2
	v_sub_u32_e32 v3, v5, v3
	v_add_u32_e32 v4, 1, v1
	v_cmp_ge_u32_e32 vcc, v3, v2
	s_nop 1
	v_cndmask_b32_e32 v1, v1, v4, vcc
	v_sub_u32_e32 v4, v3, v2
	v_cndmask_b32_e32 v3, v3, v4, vcc
	v_add_u32_e32 v4, 1, v1
	v_cmp_ge_u32_e32 vcc, v3, v2
	v_add_u32_e32 v3, 1, v5
	s_nop 0
	v_cndmask_b32_e32 v1, v1, v4, vcc
	v_mul_lo_u32 v4, v2, v1
	v_add_u32_e32 v2, v4, v2
	v_cmp_ne_u32_e32 vcc, v3, v2
	s_and_saveexec_b64 s[16:17], vcc
	s_xor_b64 s[22:23], exec, s[16:17]
	s_cbranch_execz .LBB0_1029
	s_waitcnt lgkmcnt(0)
	v_mov_b32_e32 v0, 0x6703500
	global_load_dword v0, v0, s[86:87] sc1
	s_add_u32 s28, s86, 0x6703500
	s_addc_u32 s29, s87, 0
	s_waitcnt vmcnt(0)
	v_cmp_eq_u32_e32 vcc, v0, v1
	s_and_saveexec_b64 s[24:25], vcc
	s_cbranch_execz .LBB0_1028
	s_add_u32 s26, s86, 0x6700200
	s_addc_u32 s27, s87, 0
	s_mov_b32 s14, 1
	s_mov_b64 s[36:37], 0
	v_mov_b32_e32 v0, 0
	s_branch .LBB0_1019

; __device__ __forceinline__ unsigned xb_ld(unsigned* p)              { return __hip_atomic_load(p, __ATOMIC_RELAXED, __HIP_MEMORY_SCOPE_AGENT); }
; __device__ __forceinline__ unsigned xb_add(unsigned* p, unsigned v) { return __hip_atomic_fetch_add(p, v, __ATOMIC_RELAXED, __HIP_MEMORY_SCOPE_AGENT); }
; #define XB_SPIN(cond, bar) do { unsigned _sp = 0; while (cond) { __builtin_amdgcn_s_sleep(1); \
;     if ((++_sp & 255u) == 0u) { if (xb_ld(&(bar)[XB_TMO])) break; if (_sp > XB_SPIN_CAP) { atomicAdd(&(bar)[XB_TMO], 1u); break; } } } } while (0)
; __device__ __forceinline__ void xcd_barrier(const XcdBarrier& b) {
;     ...
;         const unsigned old = xb_add(&bar[XB_XSUB(b.x)], 1u);
;         const unsigned gen = old / nloc;
;         if (old + 1u == (gen + 1u) * nloc) {
;             __builtin_amdgcn_fence(__ATOMIC_RELEASE, "agent");
;             asm volatile("s_waitcnt vmcnt(0)" ::: "memory");
;             const unsigned og = xb_add(&bar[XB_TOP], 1u);
;             const unsigned tg = og / nx;
;             if (og + 1u == (tg + 1u) * nx) xb_add(&bar[XB_TOPGEN], 1u);
;             else XB_SPIN(xb_ld(&bar[XB_TOPGEN]) == tg, bar);
;             __builtin_amdgcn_fence(__ATOMIC_ACQUIRE, "agent");
;             xb_add(&bar[XB_XGEN(b.x)], 1u);
;             asm volatile("s_waitcnt vmcnt(0)" ::: "memory");
;         } else {
;             XB_SPIN(xb_ld(&bar[XB_XGEN(b.x)]) == gen, bar);
.LBB0_1150:
	s_or_b64 exec, exec, s[12:13]
	v_cvt_f32_u32_e32 v4, v2
	s_waitcnt vmcnt(0)
	v_readfirstlane_b32 s8, v3
	v_sub_u32_e32 v3, 0, v2
	v_rcp_iflag_f32_e32 v4, v4
	v_add_u32_e32 v5, s8, v1
	v_mul_f32_e32 v4, 0x4f7ffffe, v4
	v_cvt_u32_f32_e32 v4, v4
	v_mul_lo_u32 v1, v3, v4
	v_mul_hi_u32 v1, v4, v1
	v_add_u32_e32 v1, v4, v1
	v_mul_hi_u32 v1, v5, v1
	v_mul_lo_u32 v3, v1, v2
	v_sub_u32_e32 v3, v5, v3
	v_add_u32_e32 v4, 1, v1
	v_cmp_ge_u32_e32 vcc, v3, v2
	s_nop 1
	v_cndmask_b32_e32 v1, v1, v4, vcc
	v_sub_u32_e32 v4, v3, v2
	v_cndmask_b32_e32 v3, v3, v4, vcc
	v_add_u32_e32 v4, 1, v1
	v_cmp_ge_u32_e32 vcc, v3, v2
	v_add_u32_e32 v3, 1, v5
	s_nop 0
	v_cndmask_b32_e32 v1, v1, v4, vcc
	v_mul_lo_u32 v4, v2, v1
	v_add_u32_e32 v2, v4, v2
	v_cmp_ne_u32_e32 vcc, v3, v2
	s_and_saveexec_b64 s[8:9], vcc
	s_xor_b64 s[8:9], exec, s[8:9]
	s_cbranch_execz .LBB0_1164
	s_waitcnt lgkmcnt(0)
	v_mov_b32_e32 v0, 0x6703500
	global_load_dword v0, v0, s[86:87] sc1
	s_add_u32 s24, s86, 0x6703500
	s_addc_u32 s25, s87, 0
	s_waitcnt vmcnt(0)
	v_cmp_eq_u32_e32 vcc, v0, v1
	s_and_saveexec_b64 s[12:13], vcc
	s_cbranch_execz .LBB0_1163
	s_add_u32 s22, s86, 0x6700200
	s_addc_u32 s23, s87, 0
	s_mov_b32 s14, 1
	s_mov_b64 s[26:27], 0
	v_mov_b32_e32 v0, 0
	s_branch .LBB0_1154

; __device__ __forceinline__ unsigned xb_ld(unsigned* p)              { return __hip_atomic_load(p, __ATOMIC_RELAXED, __HIP_MEMORY_SCOPE_AGENT); }
; __device__ __forceinline__ unsigned xb_add(unsigned* p, unsigned v) { return __hip_atomic_fetch_add(p, v, __ATOMIC_RELAXED, __HIP_MEMORY_SCOPE_AGENT); }
; #define XB_SPIN(cond, bar) do { unsigned _sp = 0; while (cond) { __builtin_amdgcn_s_sleep(1); \
;     if ((++_sp & 255u) == 0u) { if (xb_ld(&(bar)[XB_TMO])) break; if (_sp > XB_SPIN_CAP) { atomicAdd(&(bar)[XB_TMO], 1u); break; } } } } while (0)
; __device__ __forceinline__ void xcd_barrier(const XcdBarrier& b) {
;     ...
;         const unsigned old = xb_add(&bar[XB_XSUB(b.x)], 1u);
;         const unsigned gen = old / nloc;
;         if (old + 1u == (gen + 1u) * nloc) {
;             __builtin_amdgcn_fence(__ATOMIC_RELEASE, "agent");
;             asm volatile("s_waitcnt vmcnt(0)" ::: "memory");
;             const unsigned og = xb_add(&bar[XB_TOP], 1u);
;             const unsigned tg = og / nx;
;             if (og + 1u == (tg + 1u) * nx) xb_add(&bar[XB_TOPGEN], 1u);
;             else XB_SPIN(xb_ld(&bar[XB_TOPGEN]) == tg, bar);
;             __builtin_amdgcn_fence(__ATOMIC_ACQUIRE, "agent");
;             xb_add(&bar[XB_XGEN(b.x)], 1u);
;             asm volatile("s_waitcnt vmcnt(0)" ::: "memory");
;         } else {
;             XB_SPIN(xb_ld(&bar[XB_XGEN(b.x)]) == gen, bar);
.LBB0_1374:
	s_or_b64 exec, exec, s[12:13]
	v_cvt_f32_u32_e32 v4, v2
	s_waitcnt vmcnt(0)
	v_readfirstlane_b32 s8, v3
	v_sub_u32_e32 v3, 0, v2
	v_rcp_iflag_f32_e32 v4, v4
	v_add_u32_e32 v5, s8, v1
	v_mul_f32_e32 v4, 0x4f7ffffe, v4
	v_cvt_u32_f32_e32 v4, v4
	v_mul_lo_u32 v1, v3, v4
	v_mul_hi_u32 v1, v4, v1
	v_add_u32_e32 v1, v4, v1
	v_mul_hi_u32 v1, v5, v1
	v_mul_lo_u32 v3, v1, v2
	v_sub_u32_e32 v3, v5, v3
	v_add_u32_e32 v4, 1, v1
	v_cmp_ge_u32_e32 vcc, v3, v2
	s_nop 1
	v_cndmask_b32_e32 v1, v1, v4, vcc
	v_sub_u32_e32 v4, v3, v2
	v_cndmask_b32_e32 v3, v3, v4, vcc
	v_add_u32_e32 v4, 1, v1
	v_cmp_ge_u32_e32 vcc, v3, v2
	v_add_u32_e32 v3, 1, v5
	s_nop 0
	v_cndmask_b32_e32 v1, v1, v4, vcc
	v_mul_lo_u32 v4, v2, v1
	v_add_u32_e32 v2, v4, v2
	v_cmp_ne_u32_e32 vcc, v3, v2
	s_and_saveexec_b64 s[8:9], vcc
	s_xor_b64 s[8:9], exec, s[8:9]
	s_cbranch_execz .LBB0_1388
	s_waitcnt lgkmcnt(0)
	v_mov_b32_e32 v0, 0x6703500
	global_load_dword v0, v0, s[86:87] sc1
	s_add_u32 s28, s86, 0x6703500
	s_addc_u32 s29, s87, 0
	s_waitcnt vmcnt(0)
	v_cmp_eq_u32_e32 vcc, v0, v1
	s_and_saveexec_b64 s[12:13], vcc
	s_cbranch_execz .LBB0_1387
	s_add_u32 s26, s86, 0x6700200
	s_addc_u32 s27, s87, 0
	s_mov_b32 s14, 1
	s_mov_b64 s[36:37], 0
	v_mov_b32_e32 v0, 0
	s_branch .LBB0_1378

; __device__ __forceinline__ unsigned xb_ld(unsigned* p)              { return __hip_atomic_load(p, __ATOMIC_RELAXED, __HIP_MEMORY_SCOPE_AGENT); }
; __device__ __forceinline__ unsigned xb_add(unsigned* p, unsigned v) { return __hip_atomic_fetch_add(p, v, __ATOMIC_RELAXED, __HIP_MEMORY_SCOPE_AGENT); }
; #define XB_SPIN(cond, bar) do { unsigned _sp = 0; while (cond) { __builtin_amdgcn_s_sleep(1); \
;     if ((++_sp & 255u) == 0u) { if (xb_ld(&(bar)[XB_TMO])) break; if (_sp > XB_SPIN_CAP) { atomicAdd(&(bar)[XB_TMO], 1u); break; } } } } while (0)
; __device__ __forceinline__ void xcd_barrier(const XcdBarrier& b) {
;     ...
;         const unsigned old = xb_add(&bar[XB_XSUB(b.x)], 1u);
;         const unsigned gen = old / nloc;
;         if (old + 1u == (gen + 1u) * nloc) {
;             __builtin_amdgcn_fence(__ATOMIC_RELEASE, "agent");
;             asm volatile("s_waitcnt vmcnt(0)" ::: "memory");
;             const unsigned og = xb_add(&bar[XB_TOP], 1u);
;             const unsigned tg = og / nx;
;             if (og + 1u == (tg + 1u) * nx) xb_add(&bar[XB_TOPGEN], 1u);
;             else XB_SPIN(xb_ld(&bar[XB_TOPGEN]) == tg, bar);
;             __builtin_amdgcn_fence(__ATOMIC_ACQUIRE, "agent");
;             xb_add(&bar[XB_XGEN(b.x)], 1u);
;             asm volatile("s_waitcnt vmcnt(0)" ::: "memory");
;         } else {
;             XB_SPIN(xb_ld(&bar[XB_XGEN(b.x)]) == gen, bar);
.LBB0_1432:
	s_or_b64 exec, exec, s[8:9]
	v_cvt_f32_u32_e32 v4, v2
	s_waitcnt vmcnt(0)
	v_readfirstlane_b32 s6, v3
	v_sub_u32_e32 v3, 0, v2
	v_rcp_iflag_f32_e32 v4, v4
	v_add_u32_e32 v5, s6, v1
	v_mul_f32_e32 v4, 0x4f7ffffe, v4
	v_cvt_u32_f32_e32 v4, v4
	v_mul_lo_u32 v1, v3, v4
	v_mul_hi_u32 v1, v4, v1
	v_add_u32_e32 v1, v4, v1
	v_mul_hi_u32 v1, v5, v1
	v_mul_lo_u32 v3, v1, v2
	v_sub_u32_e32 v3, v5, v3
	v_add_u32_e32 v4, 1, v1
	v_cmp_ge_u32_e32 vcc, v3, v2
	s_nop 1
	v_cndmask_b32_e32 v1, v1, v4, vcc
	v_sub_u32_e32 v4, v3, v2
	v_cndmask_b32_e32 v3, v3, v4, vcc
	v_add_u32_e32 v4, 1, v1
	v_cmp_ge_u32_e32 vcc, v3, v2
	v_add_u32_e32 v3, 1, v5
	s_nop 0
	v_cndmask_b32_e32 v1, v1, v4, vcc
	v_mul_lo_u32 v4, v2, v1
	v_add_u32_e32 v2, v4, v2
	v_cmp_ne_u32_e32 vcc, v3, v2
	s_and_saveexec_b64 s[6:7], vcc
	s_xor_b64 s[6:7], exec, s[6:7]
	s_cbranch_execz .LBB0_1446
	s_waitcnt lgkmcnt(0)
	v_mov_b32_e32 v0, 0x6703500
	global_load_dword v0, v0, s[86:87] sc1
	s_add_u32 s20, s86, 0x6703500
	s_addc_u32 s21, s87, 0
	s_waitcnt vmcnt(0)
	v_cmp_eq_u32_e32 vcc, v0, v1
	s_and_saveexec_b64 s[8:9], vcc
	s_cbranch_execz .LBB0_1445
	s_add_u32 s12, s86, 0x6700200
	s_addc_u32 s13, s87, 0
	s_mov_b32 s14, 1
	s_mov_b64 s[26:27], 0
	v_mov_b32_e32 v0, 0
	s_branch .LBB0_1436

; __device__ __forceinline__ unsigned xb_ld(unsigned* p)              { return __hip_atomic_load(p, __ATOMIC_RELAXED, __HIP_MEMORY_SCOPE_AGENT); }
; __device__ __forceinline__ unsigned xb_add(unsigned* p, unsigned v) { return __hip_atomic_fetch_add(p, v, __ATOMIC_RELAXED, __HIP_MEMORY_SCOPE_AGENT); }
; #define XB_SPIN(cond, bar) do { unsigned _sp = 0; while (cond) { __builtin_amdgcn_s_sleep(1); \
;     if ((++_sp & 255u) == 0u) { if (xb_ld(&(bar)[XB_TMO])) break; if (_sp > XB_SPIN_CAP) { atomicAdd(&(bar)[XB_TMO], 1u); break; } } } } while (0)
; __device__ __forceinline__ void xcd_barrier(const XcdBarrier& b) {
;     ...
;         const unsigned old = xb_add(&bar[XB_XSUB(b.x)], 1u);
;         const unsigned gen = old / nloc;
;         if (old + 1u == (gen + 1u) * nloc) {
;             __builtin_amdgcn_fence(__ATOMIC_RELEASE, "agent");
;             asm volatile("s_waitcnt vmcnt(0)" ::: "memory");
;             const unsigned og = xb_add(&bar[XB_TOP], 1u);
;             const unsigned tg = og / nx;
;             if (og + 1u == (tg + 1u) * nx) xb_add(&bar[XB_TOPGEN], 1u);
;             else XB_SPIN(xb_ld(&bar[XB_TOPGEN]) == tg, bar);
;             __builtin_amdgcn_fence(__ATOMIC_ACQUIRE, "agent");
;             xb_add(&bar[XB_XGEN(b.x)], 1u);
;             asm volatile("s_waitcnt vmcnt(0)" ::: "memory");
;         } else {
;             XB_SPIN(xb_ld(&bar[XB_XGEN(b.x)]) == gen, bar);
.LBB0_1547:
	s_or_b64 exec, exec, s[8:9]
	v_cvt_f32_u32_e32 v4, v2
	s_waitcnt vmcnt(0)
	v_readfirstlane_b32 s6, v3
	v_sub_u32_e32 v3, 0, v2
	v_rcp_iflag_f32_e32 v4, v4
	v_add_u32_e32 v5, s6, v1
	v_mul_f32_e32 v4, 0x4f7ffffe, v4
	v_cvt_u32_f32_e32 v4, v4
	v_mul_lo_u32 v1, v3, v4
	v_mul_hi_u32 v1, v4, v1
	v_add_u32_e32 v1, v4, v1
	v_mul_hi_u32 v1, v5, v1
	v_mul_lo_u32 v3, v1, v2
	v_sub_u32_e32 v3, v5, v3
	v_add_u32_e32 v4, 1, v1
	v_cmp_ge_u32_e32 vcc, v3, v2
	s_nop 1
	v_cndmask_b32_e32 v1, v1, v4, vcc
	v_sub_u32_e32 v4, v3, v2
	v_cndmask_b32_e32 v3, v3, v4, vcc
	v_add_u32_e32 v4, 1, v1
	v_cmp_ge_u32_e32 vcc, v3, v2
	v_add_u32_e32 v3, 1, v5
	s_nop 0
	v_cndmask_b32_e32 v1, v1, v4, vcc
	v_mul_lo_u32 v4, v2, v1
	v_add_u32_e32 v2, v4, v2
	v_cmp_ne_u32_e32 vcc, v3, v2
	s_and_saveexec_b64 s[6:7], vcc
	s_xor_b64 s[6:7], exec, s[6:7]
	s_cbranch_execz .LBB0_1561
	s_waitcnt lgkmcnt(0)
	v_mov_b32_e32 v0, 0x6703500
	global_load_dword v0, v0, s[86:87] sc1
	s_add_u32 s12, s86, 0x6703500
	s_addc_u32 s13, s87, 0
	s_waitcnt vmcnt(0)
	v_cmp_eq_u32_e32 vcc, v0, v1
	s_and_saveexec_b64 s[8:9], vcc
	s_cbranch_execz .LBB0_1560
	s_add_u32 s10, s86, 0x6700200
	s_addc_u32 s11, s87, 0
	s_mov_b32 s14, 1
	s_mov_b64 s[18:19], 0
	v_mov_b32_e32 v0, 0
	s_branch .LBB0_1551

; __device__ __forceinline__ unsigned xb_ld(unsigned* p)              { return __hip_atomic_load(p, __ATOMIC_RELAXED, __HIP_MEMORY_SCOPE_AGENT); }
; __device__ __forceinline__ unsigned xb_add(unsigned* p, unsigned v) { return __hip_atomic_fetch_add(p, v, __ATOMIC_RELAXED, __HIP_MEMORY_SCOPE_AGENT); }
; #define XB_SPIN(cond, bar) do { unsigned _sp = 0; while (cond) { __builtin_amdgcn_s_sleep(1); \
;     if ((++_sp & 255u) == 0u) { if (xb_ld(&(bar)[XB_TMO])) break; if (_sp > XB_SPIN_CAP) { atomicAdd(&(bar)[XB_TMO], 1u); break; } } } } while (0)
; __device__ __forceinline__ void xcd_barrier(const XcdBarrier& b) {
;     ...
;         const unsigned old = xb_add(&bar[XB_XSUB(b.x)], 1u);
;         const unsigned gen = old / nloc;
;         if (old + 1u == (gen + 1u) * nloc) {
;             __builtin_amdgcn_fence(__ATOMIC_RELEASE, "agent");
;             asm volatile("s_waitcnt vmcnt(0)" ::: "memory");
;             const unsigned og = xb_add(&bar[XB_TOP], 1u);
;             const unsigned tg = og / nx;
;             if (og + 1u == (tg + 1u) * nx) xb_add(&bar[XB_TOPGEN], 1u);
;             else XB_SPIN(xb_ld(&bar[XB_TOPGEN]) == tg, bar);
;             __builtin_amdgcn_fence(__ATOMIC_ACQUIRE, "agent");
;             xb_add(&bar[XB_XGEN(b.x)], 1u);
;             asm volatile("s_waitcnt vmcnt(0)" ::: "memory");
;         } else {
;             XB_SPIN(xb_ld(&bar[XB_XGEN(b.x)]) == gen, bar);
.LBB0_1644:
	s_or_b64 exec, exec, s[10:11]
	v_cvt_f32_u32_e32 v4, v2
	s_waitcnt vmcnt(0)
	v_readfirstlane_b32 s8, v3
	v_sub_u32_e32 v3, 0, v2
	v_rcp_iflag_f32_e32 v4, v4
	v_add_u32_e32 v5, s8, v1
	v_mul_f32_e32 v4, 0x4f7ffffe, v4
	v_cvt_u32_f32_e32 v4, v4
	v_mul_lo_u32 v1, v3, v4
	v_mul_hi_u32 v1, v4, v1
	v_add_u32_e32 v1, v4, v1
	v_mul_hi_u32 v1, v5, v1
	v_mul_lo_u32 v3, v1, v2
	v_sub_u32_e32 v3, v5, v3
	v_add_u32_e32 v4, 1, v1
	v_cmp_ge_u32_e32 vcc, v3, v2
	s_nop 1
	v_cndmask_b32_e32 v1, v1, v4, vcc
	v_sub_u32_e32 v4, v3, v2
	v_cndmask_b32_e32 v3, v3, v4, vcc
	v_add_u32_e32 v4, 1, v1
	v_cmp_ge_u32_e32 vcc, v3, v2
	v_add_u32_e32 v3, 1, v5
	s_nop 0
	v_cndmask_b32_e32 v1, v1, v4, vcc
	v_mul_lo_u32 v4, v2, v1
	v_add_u32_e32 v2, v4, v2
	v_cmp_ne_u32_e32 vcc, v3, v2
	s_and_saveexec_b64 s[8:9], vcc
	s_xor_b64 s[8:9], exec, s[8:9]
	s_cbranch_execz .LBB0_1658
	s_waitcnt lgkmcnt(0)
	v_mov_b32_e32 v0, 0x6703500
	global_load_dword v0, v0, s[86:87] sc1
	s_add_u32 s18, s86, 0x6703500
	s_addc_u32 s19, s87, 0
	s_waitcnt vmcnt(0)
	v_cmp_eq_u32_e32 vcc, v0, v1
	s_and_saveexec_b64 s[10:11], vcc
	s_cbranch_execz .LBB0_1657
	s_add_u32 s12, s86, 0x6700200
	s_addc_u32 s13, s87, 0
	s_mov_b32 s14, 1
	s_mov_b64 s[20:21], 0
	v_mov_b32_e32 v0, 0
	s_branch .LBB0_1648
